# grid barrier: waiting workgroups poll one of eight per-XCD release words (bumped by the last arriver) with s_sleep 5, instead of all 512 polling the single arrival counter
# speedup vs baseline: 1.1126x; 1.0304x over previous
; __global__ void __launch_bounds__(256, 2) mega(P p, int ph_lo, int ph_hi) {
;     ...
;       grid.sync();
.LBB0_1060:
	s_or_b64 exec, exec, s[6:7]
	s_waitcnt vmcnt(0)
	v_readfirstlane_b32 s4, v2
	v_add_u32_e32 v2, -1, v0
	s_nop 0
	v_add_u32_e32 v1, s4, v1
	v_cmp_eq_u32_sdwa s[6:7], v1, v2 src0_sel:WORD_0 src1_sel:DWORD
	s_and_saveexec_b64 s[4:5], s[6:7]
	s_cbranch_execz .LBB0_1063
	s_mov_b64 s[6:7], exec
	v_mbcnt_lo_u32_b32 v2, s6, 0
	v_mbcnt_hi_u32_b32 v2, s7, v2
	v_cmp_eq_u32_e32 vcc, 0, v2
	s_and_b64 s[8:9], exec, vcc
	s_mov_b64 exec, s[8:9]
	s_cbranch_execz .LBB0_1063
	v_sub_u32_e32 v0, 0x10000, v0
	s_bcnt1_i32_b64 s6, s[6:7]
	v_mul_lo_u32 v0, v0, s6
	global_atomic_add v177, v0, s[2:3] offset:32
	v_mov_b32_e32 v248, 0x588400
	v_mov_b32_e32 v249, 1
	global_atomic_add v248, v249, s[58:59]
	v_add_u32_e32 v248, 0x1000, v248
	global_atomic_add v248, v249, s[58:59]
	v_add_u32_e32 v248, 0x1000, v248
	global_atomic_add v248, v249, s[58:59]
	v_add_u32_e32 v248, 0x1000, v248
	global_atomic_add v248, v249, s[58:59]
	v_add_u32_e32 v248, 0x1000, v248
	global_atomic_add v248, v249, s[58:59]
	v_add_u32_e32 v248, 0x1000, v248
	global_atomic_add v248, v249, s[58:59]
	v_add_u32_e32 v248, 0x1000, v248
	global_atomic_add v248, v249, s[58:59]
	v_add_u32_e32 v248, 0x1000, v248
	global_atomic_add v248, v249, s[58:59]
	v_add_u32_e32 v248, 0x1000, v248
.LBB0_1063:
	s_or_b64 exec, exec, s[4:5]
	v_readlane_b32 s4, v252, 2
	v_readlane_b32 s5, v254, 12
	v_readlane_b32 s6, v254, 13
	s_and_b32 s4, s4, 28
	s_lshl_b32 s4, s4, 10
	s_add_u32 s4, s4, 0x588400
	s_add_u32 s5, s5, s6
	v_mov_b32_e32 v0, s4
	s_nop 1
	global_load_dword v2, v0, s[58:59] sc1
	s_waitcnt vmcnt(0)
	v_cmp_gt_u32_e32 vcc, s5, v2
	s_and_b64 exec, exec, vcc
	s_cbranch_execnz .LBB0_1064
	s_getpc_b64 s[98:99]
.Lpost_getpc3:
	s_add_u32 s98, s98, (.LBB0_99-.Lpost_getpc3)&4294967295
	s_addc_u32 s99, s99, (.LBB0_99-.Lpost_getpc3)>>32
	s_setpc_b64 s[98:99]
.LBB0_1064:
	s_mov_b64 s[6:7], 0
.LBB0_1065:
	s_sleep 5
	global_load_dword v1, v0, s[58:59] sc1
	s_waitcnt vmcnt(0)
	v_cmp_le_u32_e32 vcc, s5, v1
	s_or_b64 s[6:7], vcc, s[6:7]
	s_andn2_b64 exec, exec, s[6:7]
	s_cbranch_execnz .LBB0_1065
	s_getpc_b64 s[98:99]
